# s10 + p0_fold_flat: P0 W_f fold loop flattened, all 32 w_f loads issued up front (v[130:161]), counted waits vmcnt(31..0); one round trip instead of four
# baseline (speedup 1.0000x reference)
.LBB0_24:
	s_bfe_u32 s0, s6, 0x30004
	v_lshl_or_b32 v2, s0, 4, v10
	s_ashr_i32 s24, s16, 9
	v_mul_u32_u24_e32 v12, v20, v2
	v_mul_u32_u24_e32 v31, v22, v2
	v_mul_u32_u24_e32 v32, v23, v2
	v_mul_u32_u24_e32 v33, v24, v2
	v_mul_u32_u24_e32 v34, v25, v2
	v_mul_u32_u24_e32 v35, v26, v2
	v_mul_u32_u24_e32 v36, v27, v2
	v_mul_u32_u24_e32 v37, v1, v2
	v_lshl_or_b32 v2, s24, 7, v1
	v_lshl_or_b32 v30, s0, 9, v21
	s_lshl_b32 s0, s8, 2
	v_ashrrev_i32_e32 v3, 31, v2
	s_and_b32 s0, s0, 0xfc0
	v_lshlrev_b64 v[2:3], 12, v[2:3]
	v_or_b32_e32 v2, s0, v2
	v_lshl_add_u64 v[18:19], v[14:15], 0, v[2:3]
	v_mov_b32_e32 v38, 0
	s_mov_b64 s[0:1], 0
	v_mov_b32_e32 v2, 0
	v_mov_b32_e32 v3, v13
	v_mov_b32_e32 v4, v13
	v_mov_b32_e32 v5, v13
	v_mov_b32_e32 v6, 0
	v_mov_b32_e32 v7, v13
	v_mov_b32_e32 v8, v13
	v_mov_b32_e32 v9, v13
	v_lshl_add_u64 v[40:41], v[18:19], 0, s[0:1]
	global_load_dword v130, v[40:41], off
	v_add_co_u32_e32 v42, vcc, s11, v40
	s_nop 1
	v_addc_co_u32_e32 v43, vcc, 0, v41, vcc
	global_load_dword v131, v[42:43], off
	v_add_co_u32_e32 v44, vcc, s12, v40
	s_nop 1
	v_addc_co_u32_e32 v45, vcc, 0, v41, vcc
	global_load_dword v132, v[44:45], off
	v_add_co_u32_e32 v46, vcc, s13, v40
	s_nop 1
	v_addc_co_u32_e32 v47, vcc, 0, v41, vcc
	global_load_dword v133, v[46:47], off
	v_add_co_u32_e32 v48, vcc, s14, v40
	s_nop 1
	v_addc_co_u32_e32 v49, vcc, 0, v41, vcc
	global_load_dword v134, v[48:49], off
	v_add_co_u32_e32 v50, vcc, s15, v40
	s_nop 1
	v_addc_co_u32_e32 v51, vcc, 0, v41, vcc
	global_load_dword v135, v[50:51], off
	v_add_co_u32_e32 v52, vcc, s18, v40
	s_nop 1
	v_addc_co_u32_e32 v53, vcc, 0, v41, vcc
	global_load_dword v136, v[52:53], off
	v_add_co_u32_e32 v42, vcc, s19, v40
	s_nop 1
	v_addc_co_u32_e32 v43, vcc, 0, v41, vcc
	global_load_dword v137, v[42:43], off
	s_add_u32 s0, s0, 0x20000
	s_addc_u32 s1, s1, 0
	v_lshl_add_u64 v[40:41], v[18:19], 0, s[0:1]
	global_load_dword v138, v[40:41], off
	v_add_co_u32_e32 v42, vcc, s11, v40
	s_nop 1
	v_addc_co_u32_e32 v43, vcc, 0, v41, vcc
	global_load_dword v139, v[42:43], off
	v_add_co_u32_e32 v44, vcc, s12, v40
	s_nop 1
	v_addc_co_u32_e32 v45, vcc, 0, v41, vcc
	global_load_dword v140, v[44:45], off
	v_add_co_u32_e32 v46, vcc, s13, v40
	s_nop 1
	v_addc_co_u32_e32 v47, vcc, 0, v41, vcc
	global_load_dword v141, v[46:47], off
	v_add_co_u32_e32 v48, vcc, s14, v40
	s_nop 1
	v_addc_co_u32_e32 v49, vcc, 0, v41, vcc
	global_load_dword v142, v[48:49], off
	v_add_co_u32_e32 v50, vcc, s15, v40
	s_nop 1
	v_addc_co_u32_e32 v51, vcc, 0, v41, vcc
	global_load_dword v143, v[50:51], off
	v_add_co_u32_e32 v52, vcc, s18, v40
	s_nop 1
	v_addc_co_u32_e32 v53, vcc, 0, v41, vcc
	global_load_dword v144, v[52:53], off
	v_add_co_u32_e32 v42, vcc, s19, v40
	s_nop 1
	v_addc_co_u32_e32 v43, vcc, 0, v41, vcc
	global_load_dword v145, v[42:43], off
	s_add_u32 s0, s0, 0x20000
	s_addc_u32 s1, s1, 0
	v_lshl_add_u64 v[40:41], v[18:19], 0, s[0:1]
	global_load_dword v146, v[40:41], off
	v_add_co_u32_e32 v42, vcc, s11, v40
	s_nop 1
	v_addc_co_u32_e32 v43, vcc, 0, v41, vcc
	global_load_dword v147, v[42:43], off
	v_add_co_u32_e32 v44, vcc, s12, v40
	s_nop 1
	v_addc_co_u32_e32 v45, vcc, 0, v41, vcc
	global_load_dword v148, v[44:45], off
	v_add_co_u32_e32 v46, vcc, s13, v40
	s_nop 1
	v_addc_co_u32_e32 v47, vcc, 0, v41, vcc
	global_load_dword v149, v[46:47], off
	v_add_co_u32_e32 v48, vcc, s14, v40
	s_nop 1
	v_addc_co_u32_e32 v49, vcc, 0, v41, vcc
	global_load_dword v150, v[48:49], off
	v_add_co_u32_e32 v50, vcc, s15, v40
	s_nop 1
	v_addc_co_u32_e32 v51, vcc, 0, v41, vcc
	global_load_dword v151, v[50:51], off
	v_add_co_u32_e32 v52, vcc, s18, v40
	s_nop 1
	v_addc_co_u32_e32 v53, vcc, 0, v41, vcc
	global_load_dword v152, v[52:53], off
	v_add_co_u32_e32 v42, vcc, s19, v40
	s_nop 1
	v_addc_co_u32_e32 v43, vcc, 0, v41, vcc
	global_load_dword v153, v[42:43], off
	s_add_u32 s0, s0, 0x20000
	s_addc_u32 s1, s1, 0
	v_lshl_add_u64 v[40:41], v[18:19], 0, s[0:1]
	global_load_dword v154, v[40:41], off
	v_add_co_u32_e32 v42, vcc, s11, v40
	s_nop 1
	v_addc_co_u32_e32 v43, vcc, 0, v41, vcc
	global_load_dword v155, v[42:43], off
	v_add_co_u32_e32 v44, vcc, s12, v40
	s_nop 1
	v_addc_co_u32_e32 v45, vcc, 0, v41, vcc
	global_load_dword v156, v[44:45], off
	v_add_co_u32_e32 v46, vcc, s13, v40
	s_nop 1
	v_addc_co_u32_e32 v47, vcc, 0, v41, vcc
	global_load_dword v157, v[46:47], off
	v_add_co_u32_e32 v48, vcc, s14, v40
	s_nop 1
	v_addc_co_u32_e32 v49, vcc, 0, v41, vcc
	global_load_dword v158, v[48:49], off
	v_add_co_u32_e32 v50, vcc, s15, v40
	s_nop 1
	v_addc_co_u32_e32 v51, vcc, 0, v41, vcc
	global_load_dword v159, v[50:51], off
	v_add_co_u32_e32 v52, vcc, s18, v40
	s_nop 1
	v_addc_co_u32_e32 v53, vcc, 0, v41, vcc
	global_load_dword v160, v[52:53], off
	v_add_co_u32_e32 v42, vcc, s19, v40
	s_nop 1
	v_addc_co_u32_e32 v43, vcc, 0, v41, vcc
	global_load_dword v161, v[42:43], off
	v_add_u32_e32 v39, v37, v38
	v_and_b32_e32 v39, 0x7f, v39
	v_lshl_add_u32 v39, v39, 2, s10
	ds_read2st64_b32 v[40:41], v39 offset1:2
	s_waitcnt vmcnt(31) lgkmcnt(0)
	v_mfma_f32_16x16x4_f32 v[2:5], v130, v40, v[2:5]
	v_mfma_f32_16x16x4_f32 v[6:9], v130, v41, v[6:9]
	v_add_u32_e32 v39, v36, v38
	v_and_b32_e32 v39, 0x7f, v39
	v_lshl_add_u32 v39, v39, 2, s10
	ds_read2st64_b32 v[40:41], v39 offset1:2
	s_waitcnt vmcnt(30) lgkmcnt(0)
	v_mfma_f32_16x16x4_f32 v[2:5], v131, v40, v[2:5]
	v_mfma_f32_16x16x4_f32 v[6:9], v131, v41, v[6:9]
	v_add_u32_e32 v39, v35, v38
	v_and_b32_e32 v39, 0x7f, v39
	v_lshl_add_u32 v39, v39, 2, s10
	ds_read2st64_b32 v[40:41], v39 offset1:2
	s_waitcnt vmcnt(29) lgkmcnt(0)
	v_mfma_f32_16x16x4_f32 v[2:5], v132, v40, v[2:5]
	v_mfma_f32_16x16x4_f32 v[6:9], v132, v41, v[6:9]
	v_add_u32_e32 v39, v34, v38
	v_and_b32_e32 v39, 0x7f, v39
	v_lshl_add_u32 v39, v39, 2, s10
	ds_read2st64_b32 v[40:41], v39 offset1:2
	s_waitcnt vmcnt(28) lgkmcnt(0)
	v_mfma_f32_16x16x4_f32 v[2:5], v133, v40, v[2:5]
	v_mfma_f32_16x16x4_f32 v[6:9], v133, v41, v[6:9]
	v_add_u32_e32 v39, v33, v38
	v_and_b32_e32 v39, 0x7f, v39
	v_lshl_add_u32 v39, v39, 2, s10
	ds_read2st64_b32 v[40:41], v39 offset1:2
	s_waitcnt vmcnt(27) lgkmcnt(0)
	v_mfma_f32_16x16x4_f32 v[2:5], v134, v40, v[2:5]
	v_mfma_f32_16x16x4_f32 v[6:9], v134, v41, v[6:9]
	v_add_u32_e32 v39, v32, v38
	v_and_b32_e32 v39, 0x7f, v39
	v_lshl_add_u32 v39, v39, 2, s10
	ds_read2st64_b32 v[40:41], v39 offset1:2
	s_waitcnt vmcnt(26) lgkmcnt(0)
	v_mfma_f32_16x16x4_f32 v[2:5], v135, v40, v[2:5]
	v_mfma_f32_16x16x4_f32 v[6:9], v135, v41, v[6:9]
	v_add_u32_e32 v39, v31, v38
	v_and_b32_e32 v39, 0x7f, v39
	v_lshl_add_u32 v39, v39, 2, s10
	ds_read2st64_b32 v[40:41], v39 offset1:2
	s_waitcnt vmcnt(25) lgkmcnt(0)
	v_mfma_f32_16x16x4_f32 v[2:5], v136, v40, v[2:5]
	v_mfma_f32_16x16x4_f32 v[6:9], v136, v41, v[6:9]
	v_add_u32_e32 v39, v12, v38
	v_and_b32_e32 v39, 0x7f, v39
	v_lshl_add_u32 v39, v39, 2, s10
	ds_read2st64_b32 v[40:41], v39 offset1:2
	v_add_u32_e32 v38, v38, v30
	s_waitcnt vmcnt(24) lgkmcnt(0)
	v_mfma_f32_16x16x4_f32 v[2:5], v137, v40, v[2:5]
	v_mfma_f32_16x16x4_f32 v[6:9], v137, v41, v[6:9]
	v_add_u32_e32 v39, v37, v38
	v_and_b32_e32 v39, 0x7f, v39
	v_lshl_add_u32 v39, v39, 2, s10
	ds_read2st64_b32 v[40:41], v39 offset1:2
	s_waitcnt vmcnt(23) lgkmcnt(0)
	v_mfma_f32_16x16x4_f32 v[2:5], v138, v40, v[2:5]
	v_mfma_f32_16x16x4_f32 v[6:9], v138, v41, v[6:9]
	v_add_u32_e32 v39, v36, v38
	v_and_b32_e32 v39, 0x7f, v39
	v_lshl_add_u32 v39, v39, 2, s10
	ds_read2st64_b32 v[40:41], v39 offset1:2
	s_waitcnt vmcnt(22) lgkmcnt(0)
	v_mfma_f32_16x16x4_f32 v[2:5], v139, v40, v[2:5]
	v_mfma_f32_16x16x4_f32 v[6:9], v139, v41, v[6:9]
	v_add_u32_e32 v39, v35, v38
	v_and_b32_e32 v39, 0x7f, v39
	v_lshl_add_u32 v39, v39, 2, s10
	ds_read2st64_b32 v[40:41], v39 offset1:2
	s_waitcnt vmcnt(21) lgkmcnt(0)
	v_mfma_f32_16x16x4_f32 v[2:5], v140, v40, v[2:5]
	v_mfma_f32_16x16x4_f32 v[6:9], v140, v41, v[6:9]
	v_add_u32_e32 v39, v34, v38
	v_and_b32_e32 v39, 0x7f, v39
	v_lshl_add_u32 v39, v39, 2, s10
	ds_read2st64_b32 v[40:41], v39 offset1:2
	s_waitcnt vmcnt(20) lgkmcnt(0)
	v_mfma_f32_16x16x4_f32 v[2:5], v141, v40, v[2:5]
	v_mfma_f32_16x16x4_f32 v[6:9], v141, v41, v[6:9]
	v_add_u32_e32 v39, v33, v38
	v_and_b32_e32 v39, 0x7f, v39
	v_lshl_add_u32 v39, v39, 2, s10
	ds_read2st64_b32 v[40:41], v39 offset1:2
	s_waitcnt vmcnt(19) lgkmcnt(0)
	v_mfma_f32_16x16x4_f32 v[2:5], v142, v40, v[2:5]
	v_mfma_f32_16x16x4_f32 v[6:9], v142, v41, v[6:9]
	v_add_u32_e32 v39, v32, v38
	v_and_b32_e32 v39, 0x7f, v39
	v_lshl_add_u32 v39, v39, 2, s10
	ds_read2st64_b32 v[40:41], v39 offset1:2
	s_waitcnt vmcnt(18) lgkmcnt(0)
	v_mfma_f32_16x16x4_f32 v[2:5], v143, v40, v[2:5]
	v_mfma_f32_16x16x4_f32 v[6:9], v143, v41, v[6:9]
	v_add_u32_e32 v39, v31, v38
	v_and_b32_e32 v39, 0x7f, v39
	v_lshl_add_u32 v39, v39, 2, s10
	ds_read2st64_b32 v[40:41], v39 offset1:2
	s_waitcnt vmcnt(17) lgkmcnt(0)
	v_mfma_f32_16x16x4_f32 v[2:5], v144, v40, v[2:5]
	v_mfma_f32_16x16x4_f32 v[6:9], v144, v41, v[6:9]
	v_add_u32_e32 v39, v12, v38
	v_and_b32_e32 v39, 0x7f, v39
	v_lshl_add_u32 v39, v39, 2, s10
	ds_read2st64_b32 v[40:41], v39 offset1:2
	v_add_u32_e32 v38, v38, v30
	s_waitcnt vmcnt(16) lgkmcnt(0)
	v_mfma_f32_16x16x4_f32 v[2:5], v145, v40, v[2:5]
	v_mfma_f32_16x16x4_f32 v[6:9], v145, v41, v[6:9]
	v_add_u32_e32 v39, v37, v38
	v_and_b32_e32 v39, 0x7f, v39
	v_lshl_add_u32 v39, v39, 2, s10
	ds_read2st64_b32 v[40:41], v39 offset1:2
	s_waitcnt vmcnt(15) lgkmcnt(0)
	v_mfma_f32_16x16x4_f32 v[2:5], v146, v40, v[2:5]
	v_mfma_f32_16x16x4_f32 v[6:9], v146, v41, v[6:9]
	v_add_u32_e32 v39, v36, v38
	v_and_b32_e32 v39, 0x7f, v39
	v_lshl_add_u32 v39, v39, 2, s10
	ds_read2st64_b32 v[40:41], v39 offset1:2
	s_waitcnt vmcnt(14) lgkmcnt(0)
	v_mfma_f32_16x16x4_f32 v[2:5], v147, v40, v[2:5]
	v_mfma_f32_16x16x4_f32 v[6:9], v147, v41, v[6:9]
	v_add_u32_e32 v39, v35, v38
	v_and_b32_e32 v39, 0x7f, v39
	v_lshl_add_u32 v39, v39, 2, s10
	ds_read2st64_b32 v[40:41], v39 offset1:2
	s_waitcnt vmcnt(13) lgkmcnt(0)
	v_mfma_f32_16x16x4_f32 v[2:5], v148, v40, v[2:5]
	v_mfma_f32_16x16x4_f32 v[6:9], v148, v41, v[6:9]
	v_add_u32_e32 v39, v34, v38
	v_and_b32_e32 v39, 0x7f, v39
	v_lshl_add_u32 v39, v39, 2, s10
	ds_read2st64_b32 v[40:41], v39 offset1:2
	s_waitcnt vmcnt(12) lgkmcnt(0)
	v_mfma_f32_16x16x4_f32 v[2:5], v149, v40, v[2:5]
	v_mfma_f32_16x16x4_f32 v[6:9], v149, v41, v[6:9]
	v_add_u32_e32 v39, v33, v38
	v_and_b32_e32 v39, 0x7f, v39
	v_lshl_add_u32 v39, v39, 2, s10
	ds_read2st64_b32 v[40:41], v39 offset1:2
	s_waitcnt vmcnt(11) lgkmcnt(0)
	v_mfma_f32_16x16x4_f32 v[2:5], v150, v40, v[2:5]
	v_mfma_f32_16x16x4_f32 v[6:9], v150, v41, v[6:9]
	v_add_u32_e32 v39, v32, v38
	v_and_b32_e32 v39, 0x7f, v39
	v_lshl_add_u32 v39, v39, 2, s10
	ds_read2st64_b32 v[40:41], v39 offset1:2
	s_waitcnt vmcnt(10) lgkmcnt(0)
	v_mfma_f32_16x16x4_f32 v[2:5], v151, v40, v[2:5]
	v_mfma_f32_16x16x4_f32 v[6:9], v151, v41, v[6:9]
	v_add_u32_e32 v39, v31, v38
	v_and_b32_e32 v39, 0x7f, v39
	v_lshl_add_u32 v39, v39, 2, s10
	ds_read2st64_b32 v[40:41], v39 offset1:2
	s_waitcnt vmcnt(9) lgkmcnt(0)
	v_mfma_f32_16x16x4_f32 v[2:5], v152, v40, v[2:5]
	v_mfma_f32_16x16x4_f32 v[6:9], v152, v41, v[6:9]
	v_add_u32_e32 v39, v12, v38
	v_and_b32_e32 v39, 0x7f, v39
	v_lshl_add_u32 v39, v39, 2, s10
	ds_read2st64_b32 v[40:41], v39 offset1:2
	v_add_u32_e32 v38, v38, v30
	s_waitcnt vmcnt(8) lgkmcnt(0)
	v_mfma_f32_16x16x4_f32 v[2:5], v153, v40, v[2:5]
	v_mfma_f32_16x16x4_f32 v[6:9], v153, v41, v[6:9]
	v_add_u32_e32 v39, v37, v38
	v_and_b32_e32 v39, 0x7f, v39
	v_lshl_add_u32 v39, v39, 2, s10
	ds_read2st64_b32 v[40:41], v39 offset1:2
	s_waitcnt vmcnt(7) lgkmcnt(0)
	v_mfma_f32_16x16x4_f32 v[2:5], v154, v40, v[2:5]
	v_mfma_f32_16x16x4_f32 v[6:9], v154, v41, v[6:9]
	v_add_u32_e32 v39, v36, v38
	v_and_b32_e32 v39, 0x7f, v39
	v_lshl_add_u32 v39, v39, 2, s10
	ds_read2st64_b32 v[40:41], v39 offset1:2
	s_waitcnt vmcnt(6) lgkmcnt(0)
	v_mfma_f32_16x16x4_f32 v[2:5], v155, v40, v[2:5]
	v_mfma_f32_16x16x4_f32 v[6:9], v155, v41, v[6:9]
	v_add_u32_e32 v39, v35, v38
	v_and_b32_e32 v39, 0x7f, v39
	v_lshl_add_u32 v39, v39, 2, s10
	ds_read2st64_b32 v[40:41], v39 offset1:2
	s_waitcnt vmcnt(5) lgkmcnt(0)
	v_mfma_f32_16x16x4_f32 v[2:5], v156, v40, v[2:5]
	v_mfma_f32_16x16x4_f32 v[6:9], v156, v41, v[6:9]
	v_add_u32_e32 v39, v34, v38
	v_and_b32_e32 v39, 0x7f, v39
	v_lshl_add_u32 v39, v39, 2, s10
	ds_read2st64_b32 v[40:41], v39 offset1:2
	s_waitcnt vmcnt(4) lgkmcnt(0)
	v_mfma_f32_16x16x4_f32 v[2:5], v157, v40, v[2:5]
	v_mfma_f32_16x16x4_f32 v[6:9], v157, v41, v[6:9]
	v_add_u32_e32 v39, v33, v38
	v_and_b32_e32 v39, 0x7f, v39
	v_lshl_add_u32 v39, v39, 2, s10
	ds_read2st64_b32 v[40:41], v39 offset1:2
	s_waitcnt vmcnt(3) lgkmcnt(0)
	v_mfma_f32_16x16x4_f32 v[2:5], v158, v40, v[2:5]
	v_mfma_f32_16x16x4_f32 v[6:9], v158, v41, v[6:9]
	v_add_u32_e32 v39, v32, v38
	v_and_b32_e32 v39, 0x7f, v39
	v_lshl_add_u32 v39, v39, 2, s10
	ds_read2st64_b32 v[40:41], v39 offset1:2
	s_waitcnt vmcnt(2) lgkmcnt(0)
	v_mfma_f32_16x16x4_f32 v[2:5], v159, v40, v[2:5]
	v_mfma_f32_16x16x4_f32 v[6:9], v159, v41, v[6:9]
	v_add_u32_e32 v39, v31, v38
	v_and_b32_e32 v39, 0x7f, v39
	v_lshl_add_u32 v39, v39, 2, s10
	ds_read2st64_b32 v[40:41], v39 offset1:2
	s_waitcnt vmcnt(1) lgkmcnt(0)
	v_mfma_f32_16x16x4_f32 v[2:5], v160, v40, v[2:5]
	v_mfma_f32_16x16x4_f32 v[6:9], v160, v41, v[6:9]
	v_add_u32_e32 v39, v12, v38
	v_and_b32_e32 v39, 0x7f, v39
	v_lshl_add_u32 v39, v39, 2, s10
	ds_read2st64_b32 v[40:41], v39 offset1:2
	v_add_u32_e32 v38, v38, v30
	s_waitcnt vmcnt(0) lgkmcnt(0)
	v_mfma_f32_16x16x4_f32 v[2:5], v161, v40, v[2:5]
	v_mfma_f32_16x16x4_f32 v[6:9], v161, v41, v[6:9]
	s_lshl_b32 s0, s16, 13
	s_and_b32 s0, s0, 0x3f0000
	v_lshl_or_b32 v12, v11, 1, s0
	v_readlane_b32 s0, v255, 3
	v_readlane_b32 s1, v255, 4
	s_nop 2
	v_mul_f32_e32 v2, 0x3db504f3, v2
	v_mul_f32_e32 v6, 0x3db504f3, v6
	v_lshl_add_u64 v[18:19], s[0:1], 0, v[12:13]
	s_lshl_b32 s0, s16, 5
	v_bitop3_b32 v12, s0, v29, v28 bitop3:0xc8
	v_lshl_or_b32 v30, s24, 8, v12
	v_bfe_u32 v12, v2, 16, 1
	v_ashrrev_i32_e32 v31, 31, v30
	v_add3_u32 v2, v2, v12, s20
	v_bfe_u32 v12, v6, 16, 1
	v_lshl_add_u64 v[18:19], v[30:31], 1, v[18:19]
	v_lshrrev_b32_e32 v2, 16, v2
	v_add3_u32 v6, v6, v12, s20
	v_lshl_add_u64 v[18:19], v[18:19], 0, v[16:17]
	v_and_or_b32 v2, v6, s21, v2
	global_store_dword v[18:19], v2, off offset:1024
	v_mul_f32_e32 v2, 0x3db504f3, v3
	v_mul_f32_e32 v3, 0x3db504f3, v7
	v_bfe_u32 v6, v2, 16, 1
	v_add3_u32 v2, v2, v6, s20
	v_bfe_u32 v6, v3, 16, 1
	v_lshrrev_b32_e32 v2, 16, v2
	v_add3_u32 v3, v3, v6, s20
	v_and_or_b32 v6, v3, s21, v2
	v_add_co_u32_e32 v2, vcc, s22, v18
	s_add_i32 s16, s16, s17
	s_nop 0
	v_addc_co_u32_e32 v3, vcc, 0, v19, vcc
	global_store_dword v[2:3], v6, off offset:1024
	v_mul_f32_e32 v2, 0x3db504f3, v4
	v_mul_f32_e32 v3, 0x3db504f3, v8
	v_bfe_u32 v4, v2, 16, 1
	v_add3_u32 v2, v2, v4, s20
	v_bfe_u32 v4, v3, 16, 1
	v_lshrrev_b32_e32 v2, 16, v2
	v_add3_u32 v3, v3, v4, s20
	v_and_or_b32 v4, v3, s21, v2
	v_add_co_u32_e32 v2, vcc, s23, v18
	s_add_i32 s6, s6, s7
	s_nop 0
	v_addc_co_u32_e32 v3, vcc, 0, v19, vcc
	global_store_dword v[2:3], v4, off offset:1024
	v_mul_f32_e32 v2, 0x3db504f3, v5
	v_mul_f32_e32 v3, 0x3db504f3, v9
	v_bfe_u32 v4, v2, 16, 1
	v_add3_u32 v2, v2, v4, s20
	v_bfe_u32 v4, v3, 16, 1
	v_lshrrev_b32_e32 v2, 16, v2
	v_add3_u32 v3, v3, v4, s20
	v_and_or_b32 v4, v3, s21, v2
	v_add_co_u32_e32 v2, vcc, 0x3000, v18
	s_add_i32 s8, s8, s9
	s_nop 0
	v_addc_co_u32_e32 v3, vcc, 0, v19, vcc
	s_cmpk_gt_i32 s16, 0x7ff
	global_store_dword v[2:3], v4, off offset:1024
	s_cbranch_scc0 .LBB0_24
